# wo/mixout residual GEMM phases: half of the workgroups (slot bit 0) start ~8 us late so their memory-bound epilogues interleave with the others' main loops
# baseline (speedup 1.0000x reference)
.LBB0_776:
	s_or_b64 exec, exec, s[4:5]
	s_waitcnt lgkmcnt(0)
	v_mov_b32_e32 v0, 0x21d28
	s_barrier
	v_readlane_b32 s100, v236, 1
	s_nop 3
	s_bitcmp1_b32 s100, 3
	s_cbranch_scc0 .Lresid_stagger_1
	s_sleep 127
	s_sleep 127
.Lresid_stagger_1:
	v_readlane_b32 s2, v236, 13
	v_add_u32_e32 v0, 0, v0
	ds_read_b64 v[0:1], v0
	v_mov_b32_e32 v6, v188
	s_waitcnt lgkmcnt(0)
	v_readfirstlane_b32 s27, v0
	v_mov_b32_e32 v0, 0x21d28
	v_readfirstlane_b32 s25, v1
	v_add_u32_e32 v0, 0, v0
	ds_read_b64 v[0:1], v0
	s_add_u32 s47, s27, 0x6078000
	s_addc_u32 s50, s25, 0
	s_lshl_b32 s0, s58, 21
	s_waitcnt lgkmcnt(0)
	v_readfirstlane_b32 s46, v0
	v_mov_b32_e32 v0, 0x21d20
	v_readfirstlane_b32 s33, v1
	v_add_u32_e32 v0, 0, v0
	ds_read_b64 v[0:1], v0
	s_add_u32 s0, s46, s0
	s_addc_u32 s1, s33, 0
	s_add_u32 s51, s0, 0x1700000
	s_addc_u32 s52, s1, 0
	s_waitcnt lgkmcnt(0)
	v_readfirstlane_b32 s4, v0
	v_mov_b32_e32 v0, 0x21c00
	v_readfirstlane_b32 s5, v1
	v_add_u32_e32 v0, 0, v0
	ds_read_b64 v[0:1], v0
	s_waitcnt lgkmcnt(0)
	v_readfirstlane_b32 s12, v0
	v_mov_b32_e32 v0, 0x21c08
	v_readfirstlane_b32 s13, v1
	v_add_u32_e32 v0, 0, v0
	ds_read_b64 v[0:1], v0
	s_waitcnt lgkmcnt(0)
	v_readfirstlane_b32 s8, v0
	v_mov_b32_e32 v0, 0x21d28
	v_readfirstlane_b32 s9, v1
	v_add_u32_e32 v0, 0, v0
	ds_read_b64 v[0:1], v0
	s_waitcnt lgkmcnt(0)
	v_readfirstlane_b32 s1, v0
	v_readfirstlane_b32 s0, v1
	s_add_u32 s1, s1, s2
	s_addc_u32 s0, s0, 0
	s_add_u32 s2, s1, 0x2bc2000
	s_addc_u32 s22, s0, 0
	v_readfirstlane_b32 s53, v6
	s_and_b64 vcc, exec, s[78:79]
	s_cbranch_vccnz .LBB0_800
	v_lshlrev_b32_e32 v4, 4, v6
	v_add_u32_e32 v1, 0x2000, v4
	v_ashrrev_i32_e32 v0, 31, v1
	v_lshrrev_b32_e32 v0, 22, v0
	v_add_u32_e32 v0, v1, v0
	v_ashrrev_i32_e32 v0, 10, v0
	v_lshlrev_b32_e32 v2, 5, v0
	v_and_b32_e32 v3, 32, v2
	v_mul_i32_i24_e32 v2, 0x400, v0
	v_sub_u32_e32 v1, v1, v2
	v_lshrrev_b32_e32 v2, 4, v1
	v_bitop3_b32 v2, v2, v1, 32 bitop3:0x6c
	v_ashrrev_i32_e32 v1, 31, v2
	v_lshrrev_b32_e32 v1, 26, v1
	v_add_u32_e32 v5, v2, v1
	v_ashrrev_i32_e32 v1, 6, v5
	v_and_b32_e32 v5, 0xc0, v5
	v_sub_u32_e32 v2, v2, v5
	v_lshlrev_b32_e32 v5, 3, v0
	v_ashrrev_i16_sdwa v2, v190, sext(v2) dst_sel:DWORD dst_unused:UNUSED_PAD src0_sel:DWORD src1_sel:BYTE_0
	v_and_b32_e32 v5, -16, v5
	v_bfe_i32 v2, v2, 0, 16
	v_add_u32_e32 v5, v1, v5
	v_add_u32_e32 v3, v3, v2
	v_lshlrev_b32_e32 v7, 11, v5
	v_lshl_add_u32 v132, v3, 1, v7
	v_ashrrev_i32_e32 v3, 31, v6
	v_lshrrev_b32_e32 v3, 26, v3
	v_add_u32_e32 v3, v6, v3
	s_movk_i32 s10, 0xf880
	v_ashrrev_i32_e32 v3, 6, v3
	v_mad_u64_u32 v[134:135], s[6:7], v5, s10, v[132:133]
	v_lshlrev_b32_e32 v5, 5, v3
	v_and_b32_e32 v7, 32, v5
	v_bfe_i32 v5, v6, 27, 1
	v_lshrrev_b32_e32 v5, 22, v5
	v_add_u32_e32 v5, v4, v5
	v_and_b32_e32 v5, 0xfffffc00, v5
	v_sub_u32_e32 v4, v4, v5
	v_lshrrev_b32_e32 v5, 4, v4
	v_bitop3_b32 v5, v5, v4, 32 bitop3:0x6c
	v_ashrrev_i32_e32 v4, 31, v4
	v_lshrrev_b32_e32 v4, 26, v4
	v_add_u32_e32 v4, v5, v4
	v_ashrrev_i32_e32 v4, 6, v4
	v_mul_i32_i24_e32 v8, 64, v4
	v_sub_u32_e32 v5, v5, v8
	v_lshlrev_b32_e32 v8, 3, v3
	v_ashrrev_i16_sdwa v5, v190, sext(v5) dst_sel:DWORD dst_unused:UNUSED_PAD src0_sel:DWORD src1_sel:BYTE_0
	v_and_b32_e32 v8, -16, v8
	v_bfe_i32 v5, v5, 0, 16
	v_add_u32_e32 v8, v4, v8
	v_add_u32_e32 v7, v7, v5
	v_lshlrev_b32_e32 v9, 11, v8
	v_lshl_add_u32 v164, v7, 1, v9
	s_ashr_i32 s0, s53, 6
	v_mad_u64_u32 v[136:137], s[6:7], v8, s10, v[164:165]
	s_ashr_i32 s1, s53, 8
	s_lshl_b32 s59, s0, 10
	v_readlane_b32 s6, v237, 17
	v_readlane_b32 s7, v237, 18
	s_add_u32 s10, s51, s6
	s_addc_u32 s11, s52, s7
	s_add_i32 s60, s59, 0
	s_add_i32 m0, s60, 0x10000
	v_readlane_b32 s6, v237, 13
	global_load_lds_dwordx4 v136, s[10:11]
	s_add_i32 m0, s60, 0x12000
	v_readlane_b32 s7, v237, 14
	s_add_u32 s38, s47, s6
	global_load_lds_dwordx4 v134, s[10:11]
	s_addc_u32 s39, s50, s7
	s_mov_b32 m0, s60
	s_add_i32 s61, s60, 0x2000
	global_load_lds_dwordx4 v164, s[38:39]
	s_mov_b32 m0, s61
	s_add_u32 s6, s10, 0x4000
	global_load_lds_dwordx4 v132, s[38:39]
	s_addc_u32 s7, s11, 0
	s_add_i32 m0, s60, 0x14000
	s_nop 0
	global_load_lds_dwordx4 v136, s[6:7]
	s_add_i32 m0, s60, 0x16000
	s_nop 0
	global_load_lds_dwordx4 v134, s[6:7]
	s_add_u32 s6, s38, 0x40000
	s_addc_u32 s7, s39, 0
	s_add_i32 s65, s60, 0x4000
	s_mov_b32 m0, s65
	s_add_i32 s76, s60, 0x6000
	global_load_lds_dwordx4 v164, s[6:7]
	s_mov_b32 m0, s76
	s_cmp_lg_u32 s1, 1
	global_load_lds_dwordx4 v132, s[6:7]
	s_cbranch_scc1 .LBB0_779
	s_barrier

.Lresid_stagger_0:
	v_mov_b32_e32 v2, 0x21d28
	v_add_u32_e32 v0, 0, v0
	ds_read_b64 v[0:1], v0
	v_mov_b32_e32 v4, 0x21d28
	v_add_u32_e32 v2, 0, v2
	ds_read_b64 v[2:3], v2
	s_waitcnt lgkmcnt(1)
	v_readfirstlane_b32 s44, v0
	v_mov_b32_e32 v0, 0x21d20
	v_readfirstlane_b32 s33, v1
	v_add_u32_e32 v0, 0, v0
	ds_read_b64 v[0:1], v0
	s_waitcnt lgkmcnt(1)
	v_readfirstlane_b32 s27, v2
	v_mov_b32_e32 v2, 0x21c08
	v_readfirstlane_b32 s25, v3
	s_add_u32 s45, s44, 0x15078000
	s_waitcnt lgkmcnt(0)
	v_readfirstlane_b32 s4, v0
	v_mov_b32_e32 v0, 0x21c00
	v_readfirstlane_b32 s5, v1
	v_add_u32_e32 v0, 0, v0
	ds_read_b64 v[0:1], v0
	s_addc_u32 s46, s33, 0
	v_add_u32_e32 v2, 0, v2
	ds_read_b64 v[2:3], v2
	s_lshl_b32 s0, s58, 21
	v_add_u32_e32 v4, 0, v4
	ds_read_b64 v[4:5], v4
	s_add_u32 s0, s27, s0
	s_addc_u32 s1, s25, 0
	s_add_u32 s47, s0, 0xa00000
	s_addc_u32 s50, s1, 0
	s_waitcnt lgkmcnt(0)
	v_readfirstlane_b32 s1, v4
	v_readlane_b32 s2, v236, 13
	v_readfirstlane_b32 s0, v5
	s_add_u32 s1, s1, s2
	s_addc_u32 s0, s0, 0
	s_add_u32 s2, s1, 0x2bc2000
	s_addc_u32 s22, s0, 0
	v_readlane_b32 s0, v238, 48
	v_mov_b32_e32 v6, v188
	v_readlane_b32 s1, v238, 49
	v_readfirstlane_b32 s13, v1
	v_readfirstlane_b32 s12, v0
	v_readfirstlane_b32 s9, v3
	v_readfirstlane_b32 s8, v2
	s_andn2_b64 vcc, exec, s[0:1]
	v_readfirstlane_b32 s51, v6
	s_cbranch_vccnz .LBB0_1270
	v_lshlrev_b32_e32 v4, 4, v6
	v_add_u32_e32 v1, 0x2000, v4
	v_ashrrev_i32_e32 v0, 31, v1
	v_lshrrev_b32_e32 v0, 22, v0
	v_add_u32_e32 v0, v1, v0
	v_ashrrev_i32_e32 v0, 10, v0
	v_lshlrev_b32_e32 v2, 5, v0
	v_and_b32_e32 v3, 32, v2
	v_mul_i32_i24_e32 v2, 0x400, v0
	v_sub_u32_e32 v1, v1, v2
	v_lshrrev_b32_e32 v2, 4, v1
	v_bitop3_b32 v2, v2, v1, 32 bitop3:0x6c
	v_ashrrev_i32_e32 v1, 31, v2
	v_lshrrev_b32_e32 v1, 26, v1
	v_add_u32_e32 v5, v2, v1
	v_ashrrev_i32_e32 v1, 6, v5
	v_and_b32_e32 v5, 0xc0, v5
	v_sub_u32_e32 v2, v2, v5
	v_lshlrev_b32_e32 v5, 3, v0
	v_ashrrev_i16_sdwa v2, v190, sext(v2) dst_sel:DWORD dst_unused:UNUSED_PAD src0_sel:DWORD src1_sel:BYTE_0
	v_and_b32_e32 v5, -16, v5
	v_bfe_i32 v2, v2, 0, 16
	v_add_u32_e32 v5, v1, v5
	v_add_u32_e32 v3, v3, v2
	v_lshlrev_b32_e32 v7, 11, v5
	v_lshl_add_u32 v132, v3, 1, v7
	v_ashrrev_i32_e32 v3, 31, v6
	v_lshrrev_b32_e32 v3, 26, v3
	v_add_u32_e32 v3, v6, v3
	s_movk_i32 s10, 0xf880
	v_ashrrev_i32_e32 v3, 6, v3
	v_mad_u64_u32 v[134:135], s[6:7], v5, s10, v[132:133]
	v_lshlrev_b32_e32 v5, 5, v3
	v_and_b32_e32 v7, 32, v5
	v_bfe_i32 v5, v6, 27, 1
	v_lshrrev_b32_e32 v5, 22, v5
	v_add_u32_e32 v5, v4, v5
	v_and_b32_e32 v5, 0xfffffc00, v5
	v_sub_u32_e32 v4, v4, v5
	v_lshrrev_b32_e32 v5, 4, v4
	v_bitop3_b32 v5, v5, v4, 32 bitop3:0x6c
	v_ashrrev_i32_e32 v4, 31, v4
	v_lshrrev_b32_e32 v4, 26, v4
	v_add_u32_e32 v4, v5, v4
	v_ashrrev_i32_e32 v4, 6, v4
	v_mul_i32_i24_e32 v8, 64, v4
	v_sub_u32_e32 v5, v5, v8
	v_lshlrev_b32_e32 v8, 3, v3
	v_ashrrev_i16_sdwa v5, v190, sext(v5) dst_sel:DWORD dst_unused:UNUSED_PAD src0_sel:DWORD src1_sel:BYTE_0
	v_and_b32_e32 v8, -16, v8
	v_bfe_i32 v5, v5, 0, 16
	v_add_u32_e32 v8, v4, v8
	v_add_u32_e32 v7, v7, v5
	v_lshlrev_b32_e32 v9, 11, v8
	v_lshl_add_u32 v164, v7, 1, v9
	s_ashr_i32 s0, s51, 6
	v_mad_u64_u32 v[136:137], s[6:7], v8, s10, v[164:165]
	s_ashr_i32 s1, s51, 8
	s_lshl_b32 s52, s0, 10
	v_readlane_b32 s6, v237, 17
	v_readlane_b32 s7, v237, 18
	s_add_u32 s10, s47, s6
	s_addc_u32 s11, s50, s7
	s_add_i32 s53, s52, 0
	s_add_i32 m0, s53, 0x10000
	v_readlane_b32 s6, v237, 13
	global_load_lds_dwordx4 v136, s[10:11]
	s_add_i32 m0, s53, 0x12000
	v_readlane_b32 s7, v237, 14
	s_add_u32 s36, s45, s6
	global_load_lds_dwordx4 v134, s[10:11]
	s_addc_u32 s37, s46, s7
	s_mov_b32 m0, s53
	s_add_i32 s58, s53, 0x2000
	global_load_lds_dwordx4 v164, s[36:37]
	s_mov_b32 m0, s58
	s_add_u32 s6, s10, 0x4000
	global_load_lds_dwordx4 v132, s[36:37]
	s_addc_u32 s7, s11, 0
	s_add_i32 m0, s53, 0x14000
	s_nop 0
	global_load_lds_dwordx4 v136, s[6:7]
	s_add_i32 m0, s53, 0x16000
	s_nop 0
	global_load_lds_dwordx4 v134, s[6:7]
	s_add_u32 s6, s36, 0x40000
	s_addc_u32 s7, s37, 0
	s_add_i32 s59, s53, 0x4000
	s_mov_b32 m0, s59
	s_add_i32 s60, s53, 0x6000
	global_load_lds_dwordx4 v164, s[6:7]
	s_mov_b32 m0, s60
	s_cmp_lg_u32 s1, 1
	global_load_lds_dwordx4 v132, s[6:7]
	s_cbranch_scc1 .LBB0_1249
	s_barrier
